# gMLP item end: the publish waits only for the queue atomic (vmcnt(2): the item's two stores may still be in flight)
# baseline (speedup 1.0000x reference)
.Lg_j_d:
	v_lshlrev_b32_e32 v16, 16, v2
	v_and_b32_e32 v17, 0xffff0000, v2
	v_pk_add_f32 v[8:9], v[46:47], v[8:9] op_sel_hi:[0,1]
	v_pk_mul_f32 v[8:9], v[8:9], v[16:17]
	v_pk_add_f32 v[6:7], v[46:47], v[6:7] op_sel_hi:[0,1]
	v_cvt_pk_bf16_f32 v2, v8, v9
	v_lshlrev_b32_e32 v8, 16, v3
	v_and_b32_e32 v9, 0xffff0000, v3
	v_cndmask_b32_e32 v15, v19, v22, vcc
	v_cndmask_b32_e32 v14, v18, v23, vcc
	v_pk_mul_f32 v[6:7], v[6:7], v[8:9]
	v_pk_add_f32 v[8:9], v[46:47], v[14:15] op_sel_hi:[0,1]
	v_cvt_pk_bf16_f32 v3, v6, v7
	v_lshlrev_b32_e32 v6, 16, v4
	v_and_b32_e32 v7, 0xffff0000, v4
	v_cndmask_b32_e32 v12, v20, v24, vcc
	v_pk_mul_f32 v[6:7], v[8:9], v[6:7]
	v_pk_add_f32 v[8:9], v[46:47], v[12:13] op_sel_hi:[0,1]
	v_cvt_pk_bf16_f32 v4, v6, v7
	v_lshlrev_b32_e32 v6, 16, v5
	v_and_b32_e32 v7, 0xffff0000, v5
	v_pk_mul_f32 v[6:7], v[8:9], v[6:7]
	s_nop 0
	v_cvt_pk_bf16_f32 v5, v6, v7
	global_store_dwordx4 v[10:11], v[2:5], off offset:64
	s_barrier
	s_and_saveexec_b64 s[16:17], s[44:45]
	s_cbranch_execz .LBB0_381
	s_waitcnt vmcnt(2)
	ds_write_b32 v43, v67 offset:8
	s_branch .LBB0_381
